# GEMM K-loop: s_setprio 1 during the LDS-read/DMA sections, 0 during MFMA blocks
# baseline (speedup 1.0000x reference)
; #define LDA(dst, b, h) for (int m = 0; m < 4; ++m) for (int k = 0; k < 2; ++k) \
;     dst[m][k] = *reinterpret_cast<const bf16x8*>(SA(b, h) + lds_byte(wr * 64 + m * 16 + fr, k * 32 + fq * 8))
; #define LDB(dst, b, h) for (int n = 0; n < 2; ++n) for (int k = 0; k < 2; ++k) \
;     dst[n][k] = *reinterpret_cast<const bf16x8*>(SB(b, h) + lds_byte(wc * 32 + n * 16 + fr, k * 32 + fq * 8))
; #define MMA(ai, bj, At_, Bt_) do { __builtin_amdgcn_s_setprio(1); \
;     for (int m = 0; m < 4; ++m) for (int n = 0; n < 2; ++n) for (int k = 0; k < 2; ++k) \
;       acc[ai][bj][m][n] = __builtin_amdgcn_mfma_f32_16x16x32_bf16(Bt_[n][k], At_[m][k], acc[ai][bj][m][n], 0, 0, 0); \
;     __builtin_amdgcn_s_setprio(0); } while (0)
; #define WAIT_L(n) asm volatile("s_waitcnt lgkmcnt(" #n ")" ::: "memory")
; #define BAR __builtin_amdgcn_s_barrier()
; #define SCHED __builtin_amdgcn_sched_barrier(0)
; #define STG(P, PTR, LD, O0) do { const bf16_t* _g = (PTR); \
;     __builtin_amdgcn_global_load_lds((const unsigned*)(_g + O0), (lds_u32*)((P) + swave * 1024), 16, 0, 0); \
;     __builtin_amdgcn_global_load_lds((const unsigned*)(_g + (size_t)64 * (LD) + O0), (lds_u32*)((P) + swave * 1024 + 8192), 16, 0, 0); } while (0)
; #define LDA(dst, b, h) for (int m = 0; m < 4; ++m) for (int k = 0; k < 2; ++k) \
;     dst[m][k] = *reinterpret_cast<const bf16x8*>(SA(b, h) + lds_byte(wr * 64 + m * 16 + fr, k * 32 + fq * 8))
; #define LDB(dst, b, h) for (int n = 0; n < 2; ++n) for (int k = 0; k < 2; ++k) \
;     dst[n][k] = *reinterpret_cast<const bf16x8*>(SB(b, h) + lds_byte(wc * 32 + n * 16 + fr, k * 32 + fq * 8))
; __device__ __forceinline__ void gemm_stream(int swave, const GemmJob& J, char* shm, int vb, int G) {
;     ...
;       const bool last = (t == nt - 2);
;       const bf16_t* xA = last ? nA : cA; const bf16_t* xA1 = last ? nA1 : cA1; const int k2 = last ? 0 : t + 2;
;       const bf16_t* b2 = last ? nB : cB + (size_t)(t + 2) * 64; const bf16_t* b3 = b2 + 64;
;       LDB(B0, 0, 0); SCHED; LDA(At, 0, 0); STGA(SA(1, 1), cA, cA1, t + 1, 1);
;       WAIT_L(8); BAR; WAIT_L(0); MMA(0, 0, At, B0); BAR; SCHED;
;       LDB(B1, 0, 1); STG(SB(0, 0), b2, ldb, offB0);
;       BAR; WAIT_L(0); MMA(0, 1, At, B1); BAR;
;       LDA(At, 0, 1); STGA(SA(0, 0), xA, xA1, k2, 0);
;       BAR; WAIT_L(0); MMA(1, 0, At, B0); BAR; SCHED;
;       STG(SB(0, 1), b2 + hB, ldb, offB0);
.LBB0_729:
	s_setprio 1
	ds_read_b128 v[164:167], v139
	ds_read_b128 v[168:171], v139 offset:1024
	ds_read_b128 v[172:175], v139 offset:2048
	ds_read_b128 v[176:179], v139 offset:3072
	s_cmp_eq_u32 s49, s29
	s_cselect_b64 s[68:69], -1, 0
	s_and_b64 s[64:65], s[68:69], exec
	s_cselect_b32 s52, s10, s8
	s_cselect_b32 s64, s11, s9
	s_add_i32 s33, s2, 2
	s_and_b64 s[68:69], s[68:69], exec
	s_cselect_b32 s71, s15, s21
	s_cselect_b32 s70, s14, s20
	s_cselect_b32 s68, 0, s33
	s_cselect_b32 s65, s12, s16
	s_cselect_b32 s66, s13, s17
	s_or_b32 s2, s2, 1
	s_cmp_lt_u32 s2, s36
	s_cselect_b64 vcc, -1, 0
	s_and_b64 s[2:3], vcc, exec
	s_cselect_b32 s3, 0, s36
	s_cselect_b32 s2, s38, s37
	s_not_b32 s3, s3
	s_add_i32 s94, s3, s29
	s_and_b64 s[72:73], vcc, exec
	s_cselect_b32 s3, s9, s17
	s_cselect_b32 s69, s8, s16
	s_lshl_b64 s[72:73], s[94:95], 7
	s_add_u32 s69, s69, s72
	s_addc_u32 s74, s3, s73
	s_mov_b32 s3, s95
	s_lshl_b64 s[72:73], s[2:3], 8
	s_add_u32 s72, s69, s72
	v_cndmask_b32_e32 v2, v138, v0, vcc
	s_addc_u32 s73, s74, s73
	s_add_i32 m0, s42, 0xc000
	s_lshl_b64 s[2:3], s[2:3], 7
	v_lshlrev_b64 v[212:213], 1, v[2:3]
	s_add_u32 s2, s72, s2
	v_lshl_add_u64 v[214:215], s[72:73], 0, v[212:213]
	s_addc_u32 s3, s73, s3
	ds_read_b128 v[180:183], v144
	ds_read_b128 v[188:191], v145
	ds_read_b128 v[196:199], v159
	ds_read_b128 v[204:207], v160
	global_load_lds_dwordx4 v[214:215], off
	v_lshl_add_u64 v[212:213], s[2:3], 0, v[212:213]
	s_add_i32 m0, s42, 0xe000
	s_nop 0
	global_load_lds_dwordx4 v[212:213], off
	s_waitcnt lgkmcnt(4)
	s_setprio 0
	s_barrier
	s_waitcnt lgkmcnt(0)
	v_mfma_f32_16x16x32_bf16 v[128:131], v[164:167], v[180:183], v[128:131]
	ds_read_b128 v[184:187], v144 offset:1024
	v_mfma_f32_16x16x32_bf16 v[124:127], v[172:175], v[180:183], v[124:127]
	ds_read_b128 v[192:195], v145 offset:1024
	v_mfma_f32_16x16x32_bf16 v[120:123], v[164:167], v[188:191], v[120:123]
	ds_read_b128 v[200:203], v159 offset:1024
	v_mfma_f32_16x16x32_bf16 v[116:119], v[172:175], v[188:191], v[116:119]
	ds_read_b128 v[208:211], v160 offset:1024
	v_mfma_f32_16x16x32_bf16 v[104:107], v[164:167], v[196:199], v[104:107]
	v_mfma_f32_16x16x32_bf16 v[100:103], v[172:175], v[196:199], v[100:103]
	v_mfma_f32_16x16x32_bf16 v[88:91], v[164:167], v[204:207], v[88:91]
	v_mfma_f32_16x16x32_bf16 v[84:87], v[172:175], v[204:207], v[84:87]
	s_waitcnt lgkmcnt(0)
	v_mfma_f32_16x16x32_bf16 v[128:131], v[168:171], v[184:187], v[128:131]
	v_mfma_f32_16x16x32_bf16 v[124:127], v[176:179], v[184:187], v[124:127]
	v_mfma_f32_16x16x32_bf16 v[120:123], v[168:171], v[192:195], v[120:123]
	v_mfma_f32_16x16x32_bf16 v[116:119], v[176:179], v[192:195], v[116:119]
	v_mfma_f32_16x16x32_bf16 v[104:107], v[168:171], v[200:203], v[104:107]
	v_mfma_f32_16x16x32_bf16 v[100:103], v[176:179], v[200:203], v[100:103]
	v_mfma_f32_16x16x32_bf16 v[88:91], v[168:171], v[208:211], v[88:91]
	v_mfma_f32_16x16x32_bf16 v[84:87], v[176:179], v[208:211], v[84:87]
	s_barrier
	s_setprio 1
	s_add_u32 s2, s70, s0
	s_mov_b32 m0, s43
	v_lshl_add_u64 v[228:229], s[70:71], 0, v[136:137]
	s_addc_u32 s3, s71, s1
	ds_read_b128 v[212:215], v161
	ds_read_b128 v[216:219], v161 offset:1024
	ds_read_b128 v[220:223], v161 offset:2048
	ds_read_b128 v[224:227], v161 offset:3072
	global_load_lds_dwordx4 v[228:229], off
	v_lshl_add_u64 v[230:231], s[2:3], 0, v[136:137]
	s_mov_b32 m0, s44
	s_nop 0
	global_load_lds_dwordx4 v[230:231], off
	s_setprio 0
	s_barrier
	s_waitcnt lgkmcnt(0)
	v_mfma_f32_16x16x32_bf16 v[112:115], v[212:215], v[180:183], v[112:115]
	v_mfma_f32_16x16x32_bf16 v[108:111], v[220:223], v[180:183], v[108:111]
	s_cmp_lt_u32 s68, s36
	s_cselect_b64 vcc, -1, 0
	v_mfma_f32_16x16x32_bf16 v[96:99], v[212:215], v[188:191], v[96:99]
	s_and_b64 s[70:71], vcc, exec
	s_cselect_b32 s70, s38, s37
	v_mfma_f32_16x16x32_bf16 v[92:95], v[220:223], v[188:191], v[92:95]
	s_sub_i32 s69, s68, s36
	s_min_u32 s94, s68, s69
	v_mfma_f32_16x16x32_bf16 v[80:83], v[212:215], v[196:199], v[80:83]
	s_and_b64 s[72:73], vcc, exec
	s_cselect_b32 s69, s64, s66
	v_mfma_f32_16x16x32_bf16 v[76:79], v[220:223], v[196:199], v[76:79]
	s_cselect_b32 s71, s52, s65
	s_lshl_b64 s[72:73], s[94:95], 7
	v_mfma_f32_16x16x32_bf16 v[72:75], v[212:215], v[204:207], v[72:75]
	v_cndmask_b32_e32 v2, v138, v0, vcc
	s_add_u32 s72, s71, s72
	v_mfma_f32_16x16x32_bf16 v[68:71], v[220:223], v[204:207], v[68:71]
	s_mov_b32 s71, s95
	v_mfma_f32_16x16x32_bf16 v[112:115], v[216:219], v[184:187], v[112:115]
	s_addc_u32 s73, s69, s73
	v_mfma_f32_16x16x32_bf16 v[108:111], v[224:227], v[184:187], v[108:111]
	v_lshlrev_b64 v[232:233], 1, v[2:3]
	v_mfma_f32_16x16x32_bf16 v[96:99], v[216:219], v[192:195], v[96:99]
	s_lshl_b64 s[70:71], s[70:71], 7
	v_mfma_f32_16x16x32_bf16 v[92:95], v[224:227], v[192:195], v[92:95]
	v_lshl_add_u64 v[234:235], s[72:73], 0, v[232:233]
	v_mfma_f32_16x16x32_bf16 v[80:83], v[216:219], v[200:203], v[80:83]
	s_add_u32 s72, s72, s70
	v_mfma_f32_16x16x32_bf16 v[76:79], v[224:227], v[200:203], v[76:79]
	s_mov_b32 m0, s42
	v_mfma_f32_16x16x32_bf16 v[72:75], v[216:219], v[208:211], v[72:75]
	s_addc_u32 s73, s73, s71
	v_mfma_f32_16x16x32_bf16 v[68:71], v[224:227], v[208:211], v[68:71]
	s_barrier
	s_setprio 1
	ds_read_b128 v[180:183], v144 offset:16384
	ds_read_b128 v[188:191], v145 offset:16384
	ds_read_b128 v[196:199], v159 offset:16384
	ds_read_b128 v[204:207], v160 offset:16384
	global_load_lds_dwordx4 v[234:235], off
	v_lshl_add_u64 v[234:235], s[72:73], 0, v[232:233]
	s_mov_b32 m0, s39
	s_nop 0
	global_load_lds_dwordx4 v[234:235], off
	s_setprio 0
	s_barrier
; #define LDA(dst, b, h) for (int m = 0; m < 4; ++m) for (int k = 0; k < 2; ++k) \
;     dst[m][k] = *reinterpret_cast<const bf16x8*>(SA(b, h) + lds_byte(wr * 64 + m * 16 + fr, k * 32 + fq * 8))
; #define LDB(dst, b, h) for (int n = 0; n < 2; ++n) for (int k = 0; k < 2; ++k) \
;     dst[n][k] = *reinterpret_cast<const bf16x8*>(SB(b, h) + lds_byte(wc * 32 + n * 16 + fr, k * 32 + fq * 8))
; #define MMA(ai, bj, At_, Bt_) do { __builtin_amdgcn_s_setprio(1); \
;     for (int m = 0; m < 4; ++m) for (int n = 0; n < 2; ++n) for (int k = 0; k < 2; ++k) \
;       acc[ai][bj][m][n] = __builtin_amdgcn_mfma_f32_16x16x32_bf16(Bt_[n][k], At_[m][k], acc[ai][bj][m][n], 0, 0, 0); \
;     __builtin_amdgcn_s_setprio(0); } while (0)
; #define WAIT_V(n) asm volatile("s_waitcnt vmcnt(" #n ")" ::: "memory")
; #define WAIT_L(n) asm volatile("s_waitcnt lgkmcnt(" #n ")" ::: "memory")
; #define BAR __builtin_amdgcn_s_barrier()
; #define SCHED __builtin_amdgcn_sched_barrier(0)
; #define STG(P, PTR, LD, O0) do { const bf16_t* _g = (PTR); \
;     __builtin_amdgcn_global_load_lds((const unsigned*)(_g + O0), (lds_u32*)((P) + swave * 1024), 16, 0, 0); \
;     __builtin_amdgcn_global_load_lds((const unsigned*)(_g + (size_t)64 * (LD) + O0), (lds_u32*)((P) + swave * 1024 + 8192), 16, 0, 0); } while (0)
; #define LDA(dst, b, h) for (int m = 0; m < 4; ++m) for (int k = 0; k < 2; ++k) \
;     dst[m][k] = *reinterpret_cast<const bf16x8*>(SA(b, h) + lds_byte(wr * 64 + m * 16 + fr, k * 32 + fq * 8))
; #define LDB(dst, b, h) for (int n = 0; n < 2; ++n) for (int k = 0; k < 2; ++k) \
;     dst[n][k] = *reinterpret_cast<const bf16x8*>(SB(b, h) + lds_byte(wc * 32 + n * 16 + fr, k * 32 + fq * 8))
; #define WAIT_V(n) asm volatile("s_waitcnt vmcnt(" #n ")" ::: "memory")
; #define WAIT_L(n) asm volatile("s_waitcnt lgkmcnt(" #n ")" ::: "memory")
; #define BAR __builtin_amdgcn_s_barrier()
; #define SCHED __builtin_amdgcn_sched_barrier(0)
; __device__ __forceinline__ void gemm_stream(int swave, const GemmJob& J, char* shm, int vb, int G) {
;     ...
;       BAR; WAIT_L(0); MMA(1, 0, At, B0); BAR; SCHED;
;       STG(SB(0, 1), b2 + hB, ldb, offB0);
;       WAIT_V(6); BAR; MMA(1, 1, At, B1); BAR;
;       LDB(B0, 1, 0); SCHED; LDA(At, 1, 0); STGA(SA(0, 1), xA, xA1, k2, 1);
;       WAIT_L(8); BAR; WAIT_L(0); MMA(0, 0, At, B0); BAR; SCHED;
;       LDB(B1, 1, 1); STG(SB(1, 0), b3, ldb, offB0);
	s_waitcnt lgkmcnt(0)
	v_mfma_f32_16x16x32_bf16 v[64:67], v[164:167], v[180:183], v[64:67]
	ds_read_b128 v[184:187], v144 offset:17408
	v_mfma_f32_16x16x32_bf16 v[60:63], v[172:175], v[180:183], v[60:63]
	ds_read_b128 v[192:195], v145 offset:17408
	v_mfma_f32_16x16x32_bf16 v[56:59], v[164:167], v[188:191], v[56:59]
	ds_read_b128 v[200:203], v159 offset:17408
	v_mfma_f32_16x16x32_bf16 v[52:55], v[172:175], v[188:191], v[52:55]
	ds_read_b128 v[208:211], v160 offset:17408
	v_mfma_f32_16x16x32_bf16 v[40:43], v[164:167], v[196:199], v[40:43]
	v_mfma_f32_16x16x32_bf16 v[36:39], v[172:175], v[196:199], v[36:39]
	v_mfma_f32_16x16x32_bf16 v[24:27], v[164:167], v[204:207], v[24:27]
	v_mfma_f32_16x16x32_bf16 v[20:23], v[172:175], v[204:207], v[20:23]
	s_waitcnt lgkmcnt(0)
	v_mfma_f32_16x16x32_bf16 v[64:67], v[168:171], v[184:187], v[64:67]
	v_mfma_f32_16x16x32_bf16 v[60:63], v[176:179], v[184:187], v[60:63]
	v_mfma_f32_16x16x32_bf16 v[56:59], v[168:171], v[192:195], v[56:59]
	v_mfma_f32_16x16x32_bf16 v[52:55], v[176:179], v[192:195], v[52:55]
	v_mfma_f32_16x16x32_bf16 v[40:43], v[168:171], v[200:203], v[40:43]
	v_mfma_f32_16x16x32_bf16 v[36:39], v[176:179], v[200:203], v[36:39]
	v_mfma_f32_16x16x32_bf16 v[24:27], v[168:171], v[208:211], v[24:27]
	v_mfma_f32_16x16x32_bf16 v[20:23], v[176:179], v[208:211], v[20:23]
	s_barrier
	s_setprio 1
	s_add_u32 s2, s2, s0
	s_addc_u32 s3, s3, s1
	v_lshl_add_u64 v[234:235], s[2:3], 0, v[136:137]
	s_add_u32 s2, s2, s0
	s_mov_b32 m0, s45
	s_addc_u32 s3, s3, s1
	global_load_lds_dwordx4 v[234:235], off
	v_lshl_add_u64 v[236:237], s[2:3], 0, v[136:137]
	s_mov_b32 m0, s46
	s_nop 0
	global_load_lds_dwordx4 v[236:237], off
	s_waitcnt vmcnt(6)
	s_setprio 0
	s_barrier
	v_mfma_f32_16x16x32_bf16 v[48:51], v[212:215], v[180:183], v[48:51]
	v_mfma_f32_16x16x32_bf16 v[44:47], v[220:223], v[180:183], v[44:47]
	v_mfma_f32_16x16x32_bf16 v[32:35], v[212:215], v[188:191], v[32:35]
	v_mfma_f32_16x16x32_bf16 v[28:31], v[220:223], v[188:191], v[28:31]
	v_mfma_f32_16x16x32_bf16 v[16:19], v[212:215], v[196:199], v[16:19]
	v_mfma_f32_16x16x32_bf16 v[12:15], v[220:223], v[196:199], v[12:15]
	v_mfma_f32_16x16x32_bf16 v[8:11], v[212:215], v[204:207], v[8:11]
	v_mfma_f32_16x16x32_bf16 v[4:7], v[220:223], v[204:207], v[4:7]
	v_mfma_f32_16x16x32_bf16 v[48:51], v[216:219], v[184:187], v[48:51]
	v_mfma_f32_16x16x32_bf16 v[44:47], v[224:227], v[184:187], v[44:47]
	v_mfma_f32_16x16x32_bf16 v[32:35], v[216:219], v[192:195], v[32:35]
	v_mfma_f32_16x16x32_bf16 v[28:31], v[224:227], v[192:195], v[28:31]
	v_mfma_f32_16x16x32_bf16 v[16:19], v[216:219], v[200:203], v[16:19]
	v_mfma_f32_16x16x32_bf16 v[12:15], v[224:227], v[200:203], v[12:15]
	v_mfma_f32_16x16x32_bf16 v[8:11], v[216:219], v[208:211], v[8:11]
	v_mfma_f32_16x16x32_bf16 v[4:7], v[224:227], v[208:211], v[4:7]
	s_barrier
	s_setprio 1
	ds_read_b128 v[164:167], v162
	ds_read_b128 v[168:171], v162 offset:1024
	ds_read_b128 v[172:175], v162 offset:2048
	ds_read_b128 v[176:179], v162 offset:3072
	s_add_u32 s2, s72, s70
	s_addc_u32 s3, s73, s71
	v_lshl_add_u64 v[212:213], s[2:3], 0, v[232:233]
	s_add_u32 s2, s2, s70
	s_mov_b32 m0, s47
	s_addc_u32 s3, s3, s71
	ds_read_b128 v[180:183], v144 offset:32768
	ds_read_b128 v[188:191], v145 offset:32768
	ds_read_b128 v[196:199], v159 offset:32768
	ds_read_b128 v[204:207], v160 offset:32768
	global_load_lds_dwordx4 v[212:213], off
	v_lshl_add_u64 v[212:213], s[2:3], 0, v[232:233]
	s_mov_b32 m0, s48
	s_nop 0
	global_load_lds_dwordx4 v[212:213], off
	s_waitcnt lgkmcnt(4)
	s_setprio 0
	s_barrier
	s_waitcnt lgkmcnt(0)
	v_mfma_f32_16x16x32_bf16 v[128:131], v[164:167], v[180:183], v[128:131]
	ds_read_b128 v[184:187], v144 offset:33792
	v_mfma_f32_16x16x32_bf16 v[124:127], v[172:175], v[180:183], v[124:127]
	ds_read_b128 v[192:195], v145 offset:33792
	v_mfma_f32_16x16x32_bf16 v[120:123], v[164:167], v[188:191], v[120:123]
	ds_read_b128 v[200:203], v159 offset:33792
	v_mfma_f32_16x16x32_bf16 v[116:119], v[172:175], v[188:191], v[116:119]
	ds_read_b128 v[208:211], v160 offset:33792
	v_mfma_f32_16x16x32_bf16 v[104:107], v[164:167], v[196:199], v[104:107]
	v_mfma_f32_16x16x32_bf16 v[100:103], v[172:175], v[196:199], v[100:103]
	v_mfma_f32_16x16x32_bf16 v[88:91], v[164:167], v[204:207], v[88:91]
	v_mfma_f32_16x16x32_bf16 v[84:87], v[172:175], v[204:207], v[84:87]
	s_waitcnt lgkmcnt(0)
	v_mfma_f32_16x16x32_bf16 v[128:131], v[168:171], v[184:187], v[128:131]
	v_mfma_f32_16x16x32_bf16 v[124:127], v[176:179], v[184:187], v[124:127]
	v_mfma_f32_16x16x32_bf16 v[120:123], v[168:171], v[192:195], v[120:123]
	v_mfma_f32_16x16x32_bf16 v[116:119], v[176:179], v[192:195], v[116:119]
	v_mfma_f32_16x16x32_bf16 v[104:107], v[168:171], v[200:203], v[104:107]
	v_mfma_f32_16x16x32_bf16 v[100:103], v[176:179], v[200:203], v[100:103]
	v_mfma_f32_16x16x32_bf16 v[88:91], v[168:171], v[208:211], v[88:91]
	v_mfma_f32_16x16x32_bf16 v[84:87], v[176:179], v[208:211], v[84:87]
	s_barrier
	s_setprio 1
	v_lshl_add_u64 v[228:229], v[228:229], 0, s[22:23]
	s_add_i32 m0, s42, 0x18000
	ds_read_b128 v[212:215], v163
	ds_read_b128 v[216:219], v163 offset:1024
	ds_read_b128 v[220:223], v163 offset:2048
	ds_read_b128 v[224:227], v163 offset:3072
	global_load_lds_dwordx4 v[228:229], off
	v_lshl_add_u64 v[228:229], v[230:231], 0, s[22:23]
	s_add_i32 m0, s42, 0x1a000
	s_nop 0
	global_load_lds_dwordx4 v[228:229], off
	s_setprio 0
	s_barrier
; #define LDA(dst, b, h) for (int m = 0; m < 4; ++m) for (int k = 0; k < 2; ++k) \
;     dst[m][k] = *reinterpret_cast<const bf16x8*>(SA(b, h) + lds_byte(wr * 64 + m * 16 + fr, k * 32 + fq * 8))
; #define MMA(ai, bj, At_, Bt_) do { __builtin_amdgcn_s_setprio(1); \
;     for (int m = 0; m < 4; ++m) for (int n = 0; n < 2; ++n) for (int k = 0; k < 2; ++k) \
;       acc[ai][bj][m][n] = __builtin_amdgcn_mfma_f32_16x16x32_bf16(Bt_[n][k], At_[m][k], acc[ai][bj][m][n], 0, 0, 0); \
;     __builtin_amdgcn_s_setprio(0); } while (0)
; #define WAIT_V(n) asm volatile("s_waitcnt vmcnt(" #n ")" ::: "memory")
; #define WAIT_L(n) asm volatile("s_waitcnt lgkmcnt(" #n ")" ::: "memory")
; #define BAR __builtin_amdgcn_s_barrier()
; #define SCHED __builtin_amdgcn_sched_barrier(0)
; #define STG(P, PTR, LD, O0) do { const bf16_t* _g = (PTR); \
;     __builtin_amdgcn_global_load_lds((const unsigned*)(_g + O0), (lds_u32*)((P) + swave * 1024), 16, 0, 0); \
;     __builtin_amdgcn_global_load_lds((const unsigned*)(_g + (size_t)64 * (LD) + O0), (lds_u32*)((P) + swave * 1024 + 8192), 16, 0, 0); } while (0)
; #define LDA(dst, b, h) for (int m = 0; m < 4; ++m) for (int k = 0; k < 2; ++k) \
;     dst[m][k] = *reinterpret_cast<const bf16x8*>(SA(b, h) + lds_byte(wr * 64 + m * 16 + fr, k * 32 + fq * 8))
; #define MMA(ai, bj, At_, Bt_) do { __builtin_amdgcn_s_setprio(1); \
;     for (int m = 0; m < 4; ++m) for (int n = 0; n < 2; ++n) for (int k = 0; k < 2; ++k) \
;       acc[ai][bj][m][n] = __builtin_amdgcn_mfma_f32_16x16x32_bf16(Bt_[n][k], At_[m][k], acc[ai][bj][m][n], 0, 0, 0); \
;     __builtin_amdgcn_s_setprio(0); } while (0)
; #define WAIT_V(n) asm volatile("s_waitcnt vmcnt(" #n ")" ::: "memory")
; #define WAIT_L(n) asm volatile("s_waitcnt lgkmcnt(" #n ")" ::: "memory")
; #define BAR __builtin_amdgcn_s_barrier()
; #define SCHED __builtin_amdgcn_sched_barrier(0)
; __device__ __forceinline__ void gemm_stream(int swave, const GemmJob& J, char* shm, int vb, int G) {
;     ...
;       BAR; WAIT_L(0); MMA(0, 1, At, B1); BAR;
;       LDA(At, 1, 1); STGA(SA(1, 0), xA, xA1, k2 + 1, 0);
;       BAR; WAIT_L(0); MMA(1, 0, At, B0); BAR; SCHED;
;       STG(SB(1, 1), b3 + hB, ldb, offB0);
;       WAIT_V(6); BAR; MMA(1, 1, At, B1); BAR;
	s_waitcnt lgkmcnt(0)
	v_mfma_f32_16x16x32_bf16 v[112:115], v[212:215], v[180:183], v[112:115]
	v_mfma_f32_16x16x32_bf16 v[108:111], v[220:223], v[180:183], v[108:111]
	s_or_b32 s68, s68, 1
	s_cmp_lt_u32 s68, s36
	v_mfma_f32_16x16x32_bf16 v[96:99], v[212:215], v[188:191], v[96:99]
	s_cselect_b64 vcc, -1, 0
	s_and_b64 s[2:3], vcc, exec
	v_mfma_f32_16x16x32_bf16 v[92:95], v[220:223], v[188:191], v[92:95]
	s_cselect_b32 s69, s38, s37
	s_sub_i32 s2, s68, s36
	v_mfma_f32_16x16x32_bf16 v[80:83], v[212:215], v[196:199], v[80:83]
	s_min_u32 s94, s68, s2
	s_and_b64 s[2:3], vcc, exec
	v_mfma_f32_16x16x32_bf16 v[76:79], v[220:223], v[196:199], v[76:79]
	s_cselect_b32 s64, s64, s66
	s_cselect_b32 s52, s52, s65
	v_mfma_f32_16x16x32_bf16 v[72:75], v[212:215], v[204:207], v[72:75]
	s_lshl_b64 s[2:3], s[94:95], 7
	v_cndmask_b32_e32 v2, v138, v0, vcc
	v_mfma_f32_16x16x32_bf16 v[68:71], v[220:223], v[204:207], v[68:71]
	s_add_u32 s2, s52, s2
	v_mfma_f32_16x16x32_bf16 v[112:115], v[216:219], v[184:187], v[112:115]
	s_addc_u32 s3, s64, s3
	v_mfma_f32_16x16x32_bf16 v[108:111], v[224:227], v[184:187], v[108:111]
	v_lshlrev_b64 v[228:229], 1, v[2:3]
	v_mfma_f32_16x16x32_bf16 v[96:99], v[216:219], v[192:195], v[96:99]
	s_lshl_b32 s52, s69, 7
	v_mfma_f32_16x16x32_bf16 v[92:95], v[224:227], v[192:195], v[92:95]
	v_lshl_add_u64 v[230:231], s[2:3], 0, v[228:229]
	v_mfma_f32_16x16x32_bf16 v[80:83], v[216:219], v[200:203], v[80:83]
	s_add_u32 s2, s2, s52
	v_mfma_f32_16x16x32_bf16 v[76:79], v[224:227], v[200:203], v[76:79]
	s_mov_b32 m0, s54
	v_mfma_f32_16x16x32_bf16 v[72:75], v[216:219], v[208:211], v[72:75]
	s_addc_u32 s3, s3, 0
	v_mfma_f32_16x16x32_bf16 v[68:71], v[224:227], v[208:211], v[68:71]
	s_barrier
	s_setprio 1
	ds_read_b128 v[180:183], v144 offset:49152
	ds_read_b128 v[188:191], v145 offset:49152
	ds_read_b128 v[196:199], v159 offset:49152
	ds_read_b128 v[204:207], v160 offset:49152
	global_load_lds_dwordx4 v[230:231], off
	v_lshl_add_u64 v[228:229], s[2:3], 0, v[228:229]
	s_mov_b32 m0, s55
	s_nop 0
	global_load_lds_dwordx4 v[228:229], off
	s_setprio 0
	s_barrier
	s_waitcnt lgkmcnt(0)
	v_mfma_f32_16x16x32_bf16 v[64:67], v[164:167], v[180:183], v[64:67]
	ds_read_b128 v[184:187], v144 offset:50176
	v_mfma_f32_16x16x32_bf16 v[60:63], v[172:175], v[180:183], v[60:63]
	ds_read_b128 v[192:195], v145 offset:50176
	v_mfma_f32_16x16x32_bf16 v[56:59], v[164:167], v[188:191], v[56:59]
	ds_read_b128 v[200:203], v159 offset:50176
	v_mfma_f32_16x16x32_bf16 v[52:55], v[172:175], v[188:191], v[52:55]
	ds_read_b128 v[208:211], v160 offset:50176
	v_mfma_f32_16x16x32_bf16 v[40:43], v[164:167], v[196:199], v[40:43]
	v_mfma_f32_16x16x32_bf16 v[36:39], v[172:175], v[196:199], v[36:39]
	v_mfma_f32_16x16x32_bf16 v[24:27], v[164:167], v[204:207], v[24:27]
	v_mfma_f32_16x16x32_bf16 v[20:23], v[172:175], v[204:207], v[20:23]
	s_waitcnt lgkmcnt(0)
	v_mfma_f32_16x16x32_bf16 v[64:67], v[168:171], v[184:187], v[64:67]
	v_mfma_f32_16x16x32_bf16 v[60:63], v[176:179], v[184:187], v[60:63]
	v_mfma_f32_16x16x32_bf16 v[56:59], v[168:171], v[192:195], v[56:59]
	v_mfma_f32_16x16x32_bf16 v[52:55], v[176:179], v[192:195], v[52:55]
	v_mfma_f32_16x16x32_bf16 v[40:43], v[168:171], v[200:203], v[40:43]
	v_mfma_f32_16x16x32_bf16 v[36:39], v[176:179], v[200:203], v[36:39]
	v_mfma_f32_16x16x32_bf16 v[24:27], v[168:171], v[208:211], v[24:27]
	v_mfma_f32_16x16x32_bf16 v[20:23], v[176:179], v[208:211], v[20:23]
	s_barrier
	s_setprio 1
	v_lshl_add_u64 v[164:165], v[234:235], 0, s[22:23]
	s_add_i32 m0, s42, 0x1c000
	s_nop 0
	global_load_lds_dwordx4 v[164:165], off
	v_lshl_add_u64 v[164:165], v[236:237], 0, s[22:23]
	s_add_i32 m0, s42, 0x1e000
	s_nop 0
	global_load_lds_dwordx4 v[164:165], off
	s_waitcnt vmcnt(6)
	s_setprio 0
	s_barrier
	v_mfma_f32_16x16x32_bf16 v[48:51], v[212:215], v[180:183], v[48:51]
	v_mfma_f32_16x16x32_bf16 v[44:47], v[220:223], v[180:183], v[44:47]
	s_add_i32 s29, s29, 2
	v_mfma_f32_16x16x32_bf16 v[32:35], v[212:215], v[188:191], v[32:35]
	s_add_u32 s20, s20, 0x100
	v_mfma_f32_16x16x32_bf16 v[28:31], v[220:223], v[188:191], v[28:31]
	s_addc_u32 s21, s21, 0
	v_mfma_f32_16x16x32_bf16 v[16:19], v[212:215], v[196:199], v[16:19]
	s_cmp_ge_u32 s33, s49
	v_mfma_f32_16x16x32_bf16 v[12:15], v[220:223], v[196:199], v[12:15]
	s_mov_b32 s2, s33
	v_mfma_f32_16x16x32_bf16 v[8:11], v[212:215], v[204:207], v[8:11]
	v_mfma_f32_16x16x32_bf16 v[4:7], v[220:223], v[204:207], v[4:7]
	v_mfma_f32_16x16x32_bf16 v[48:51], v[216:219], v[184:187], v[48:51]
	v_mfma_f32_16x16x32_bf16 v[44:47], v[224:227], v[184:187], v[44:47]
	v_mfma_f32_16x16x32_bf16 v[32:35], v[216:219], v[192:195], v[32:35]
	v_mfma_f32_16x16x32_bf16 v[28:31], v[224:227], v[192:195], v[28:31]
	v_mfma_f32_16x16x32_bf16 v[16:19], v[216:219], v[200:203], v[16:19]
	v_mfma_f32_16x16x32_bf16 v[12:15], v[224:227], v[200:203], v[12:15]
	v_mfma_f32_16x16x32_bf16 v[8:11], v[216:219], v[208:211], v[8:11]
	v_mfma_f32_16x16x32_bf16 v[4:7], v[224:227], v[208:211], v[4:7]
	s_barrier
; __device__ __forceinline__ unsigned pk2(float lo, float hi) { f32x2_t v = {lo, hi}; bf16x2_t b = __builtin_convertvector(v, bf16x2_t); return __builtin_bit_cast(unsigned, b); }
; #define WAIT_V(n) asm volatile("s_waitcnt vmcnt(" #n ")" ::: "memory")
; #define BAR __builtin_amdgcn_s_barrier()
; #define WAIT_V(n) asm volatile("s_waitcnt vmcnt(" #n ")" ::: "memory")
; #define BAR __builtin_amdgcn_s_barrier()
; __device__ __forceinline__ void gemm_stream(int swave, const GemmJob& J, char* shm, int vb, int G) {
;     ...
;     {
;       bf16_t* C = (bf16_t*)((char*)J.c0 + (size_t)cg * J.strideC);
; #pragma unroll
;       for (int ai = 0; ai < 2; ++ai)
; #pragma unroll
;         for (int m = 0; m < 4; ++m)
; #pragma unroll
;           for (int bj = 0; bj < 2; ++bj) {
;             const f32x4 v0 = acc[ai][bj][m][0], v1 = acc[ai][bj][m][1];
;             uint4 o; o.x = pk2(v0[0], v0[1]); o.y = pk2(v0[2], v0[3]); o.z = pk2(v1[0], v1[1]); o.w = pk2(v1[2], v1[3]);
;             *(uint4*)(C + (size_t)(cbrow + ai * 128 + wr * 64 + m * 16 + fr) * J.ldc + cbcol + bj * 128 + wc * 32 + fq * 8) = o;
;           }
;     }
;     if (!has_next) break;
; #pragma unroll
;     for (int a_ = 0; a_ < 2; ++a_)
; #pragma unroll
;       for (int b_ = 0; b_ < 2; ++b_)
; #pragma unroll
;         for (int m = 0; m < 4; ++m)
; #pragma unroll
;           for (int n = 0; n < 2; ++n) acc[a_][b_][m][n] = (f32x4){0.f, 0.f, 0.f, 0.f};
;     id = nid; cg = ng; cbrow = nbrow; cbcol = nbcol; cA = nA; cA1 = nA1; cB = nB;
;   }
;   WAIT_V(0);
;   if (wr == 0) BAR;
	s_cbranch_scc0 .LBB0_729
	v_add_u32_e32 v164, s5, v1
	s_ashr_i32 s5, s4, 31
	s_lshl_b64 s[2:3], s[4:5], 1
	v_ashrrev_i32_e32 v2, 31, v164
	s_add_u32 s2, s50, s2
	v_cvt_pk_bf16_f32 v128, v128, v129
	v_cvt_pk_bf16_f32 v129, v130, v131
	v_cvt_pk_bf16_f32 v130, v124, v125
	v_mul_lo_u32 v2, v2, s18
	v_mad_u64_u32 v[124:125], s[4:5], v164, s18, 0
	s_addc_u32 s3, s51, s3
	v_add_u32_e32 v125, v125, v2
	v_lshl_add_u64 v[124:125], v[124:125], 1, s[2:3]
	v_mov_b32_e32 v141, v3
	v_lshl_add_u64 v[124:125], v[124:125], 0, v[140:141]
	v_mov_b32_e32 v143, v3
	v_lshl_add_u64 v[124:125], v[124:125], 0, v[142:143]
	s_lshl_b32 s2, s18, 5
	s_mov_b32 s3, 0
	s_mul_i32 s4, s18, 0xa0
	s_mov_b32 s5, 0
	v_cvt_pk_bf16_f32 v112, v112, v113
	v_cvt_pk_bf16_f32 v113, v114, v115
	v_cvt_pk_bf16_f32 v114, v108, v109
	v_cvt_pk_bf16_f32 v115, v110, v111
	global_store_dwordx4 v[124:125], v[112:115], off offset:256
	v_cvt_pk_bf16_f32 v131, v126, v127
	v_cvt_pk_bf16_f32 v96, v96, v97
	v_lshl_add_u64 v[112:113], v[124:125], 0, s[2:3]
	v_cvt_pk_bf16_f32 v97, v98, v99
	v_cvt_pk_bf16_f32 v98, v92, v93
	v_cvt_pk_bf16_f32 v99, v94, v95
	global_store_dwordx4 v[124:125], v[128:131], off
	global_store_dwordx4 v[112:113], v[96:99], off offset:256
	v_cvt_pk_bf16_f32 v108, v120, v121
	v_cvt_pk_bf16_f32 v109, v122, v123
	v_lshl_add_u64 v[96:97], v[112:113], 0, s[2:3]
	v_cvt_pk_bf16_f32 v110, v116, v117
	v_cvt_pk_bf16_f32 v111, v118, v119
	v_cvt_pk_bf16_f32 v80, v80, v81
	v_cvt_pk_bf16_f32 v81, v82, v83
	v_cvt_pk_bf16_f32 v82, v76, v77
	v_cvt_pk_bf16_f32 v83, v78, v79
	global_store_dwordx4 v[112:113], v[108:111], off
	global_store_dwordx4 v[96:97], v[80:83], off offset:256
	v_cvt_pk_bf16_f32 v64, v64, v65
	v_cvt_pk_bf16_f32 v65, v66, v67
	v_lshl_add_u64 v[80:81], v[96:97], 0, s[2:3]
	v_cvt_pk_bf16_f32 v66, v60, v61
	v_lshl_add_u64 v[60:61], v[80:81], 0, s[4:5]
	v_cvt_pk_bf16_f32 v72, v72, v73
	v_cvt_pk_bf16_f32 v73, v74, v75
	v_cvt_pk_bf16_f32 v74, v68, v69
	v_cvt_pk_bf16_f32 v67, v62, v63
	v_cvt_pk_bf16_f32 v92, v104, v105
	v_cvt_pk_bf16_f32 v93, v106, v107
	v_cvt_pk_bf16_f32 v94, v100, v101
	v_cvt_pk_bf16_f32 v95, v102, v103
	v_cvt_pk_bf16_f32 v76, v88, v89
	v_cvt_pk_bf16_f32 v77, v90, v91
	v_cvt_pk_bf16_f32 v78, v84, v85
	v_cvt_pk_bf16_f32 v79, v86, v87
	v_cvt_pk_bf16_f32 v75, v70, v71
	v_cvt_pk_bf16_f32 v48, v48, v49
	v_cvt_pk_bf16_f32 v49, v50, v51
	v_cvt_pk_bf16_f32 v50, v44, v45
	v_cvt_pk_bf16_f32 v51, v46, v47
	global_store_dwordx4 v[96:97], v[92:95], off
	global_store_dwordx4 v[80:81], v[76:79], off
	global_store_dwordx4 v[80:81], v[72:75], off offset:256
	global_store_dwordx4 v[60:61], v[48:51], off offset:256
	v_cvt_pk_bf16_f32 v32, v32, v33
	v_cvt_pk_bf16_f32 v33, v34, v35
	v_lshl_add_u64 v[48:49], v[60:61], 0, s[2:3]
	v_cvt_pk_bf16_f32 v34, v28, v29
	v_cvt_pk_bf16_f32 v35, v30, v31
	global_store_dwordx4 v[60:61], v[64:67], off
	global_store_dwordx4 v[48:49], v[32:35], off offset:256
	v_cvt_pk_bf16_f32 v44, v56, v57
	v_cvt_pk_bf16_f32 v45, v58, v59
	v_lshl_add_u64 v[32:33], v[48:49], 0, s[2:3]
	v_cvt_pk_bf16_f32 v46, v52, v53
	v_cvt_pk_bf16_f32 v47, v54, v55
	v_cvt_pk_bf16_f32 v16, v16, v17
	v_cvt_pk_bf16_f32 v17, v18, v19
	v_cvt_pk_bf16_f32 v18, v12, v13
	v_cvt_pk_bf16_f32 v19, v14, v15
	global_store_dwordx4 v[48:49], v[44:47], off
	global_store_dwordx4 v[32:33], v[16:19], off offset:256
	v_cvt_pk_bf16_f32 v28, v40, v41
	v_cvt_pk_bf16_f32 v29, v42, v43
	v_lshl_add_u64 v[16:17], v[32:33], 0, s[2:3]
	v_cvt_pk_bf16_f32 v30, v36, v37
	v_cvt_pk_bf16_f32 v31, v38, v39
	v_cvt_pk_bf16_f32 v12, v24, v25
	v_cvt_pk_bf16_f32 v13, v26, v27
	v_cvt_pk_bf16_f32 v14, v20, v21
	v_cvt_pk_bf16_f32 v15, v22, v23
	v_cvt_pk_bf16_f32 v8, v8, v9
	v_cvt_pk_bf16_f32 v9, v10, v11
	v_cvt_pk_bf16_f32 v10, v4, v5
	v_cvt_pk_bf16_f32 v11, v6, v7
	s_and_b64 vcc, exec, s[6:7]
	s_mov_b64 s[2:3], s[14:15]
	s_mov_b64 s[16:17], s[12:13]
	s_mov_b64 s[8:9], s[10:11]
	s_mov_b32 s4, s56
	s_mov_b32 s5, s28
	global_store_dwordx4 v[32:33], v[28:31], off
	global_store_dwordx4 v[16:17], v[12:15], off
	global_store_dwordx4 v[16:17], v[8:11], off offset:256
	s_cbranch_vccz .LBB0_726
	s_waitcnt vmcnt(0)
	s_movk_i32 s66, 0x100
	v_cmp_gt_u32_e32 vcc, s66, v135
	s_and_saveexec_b64 s[0:1], vcc
	s_cbranch_execz .LBB0_733
	s_barrier
